# attention: waves 4-7 run the P.V MFMAs one barrier interval late (three V slots, third in the idle Q LDS), desynchronising the LDS-bound and VALU-bound phases of SIMD partners
# baseline (speedup 1.0000x reference)
.LBB0_223:
	s_cmp_lt_u32 s97, 4
	s_cbranch_scc1 .Latt_exit_nopv
	s_sub_i32 s0, s39, 63
	s_cmp_gt_u32 s0, s41
	s_cbranch_scc1 .Latt_exit_nopv
	s_sub_i32 s0, s91, 0x8800
	s_cmp_eq_u32 s91, 0
	s_cselect_b32 s0, 0x11000, s0
	v_add_u32_e32 v238, s0, v179
	ds_read_b64_tr_b16 v[214:215], v238 offset:17408
	ds_read_b64_tr_b16 v[216:217], v238 offset:26112
	ds_read_b64_tr_b16 v[218:219], v238 offset:17440
	ds_read_b64_tr_b16 v[220:221], v238 offset:26144
	ds_read_b64_tr_b16 v[202:203], v238 offset:17472
	ds_read_b64_tr_b16 v[204:205], v238 offset:26176
	ds_read_b64_tr_b16 v[210:211], v238 offset:17504
	ds_read_b64_tr_b16 v[212:213], v238 offset:26208
	ds_read_b64_tr_b16 v[224:225], v238 offset:17536
	ds_read_b64_tr_b16 v[226:227], v238 offset:26240
	ds_read_b64_tr_b16 v[228:229], v238 offset:17568
	ds_read_b64_tr_b16 v[230:231], v238 offset:26272
	ds_read_b64_tr_b16 v[232:233], v238 offset:17600
	ds_read_b64_tr_b16 v[234:235], v238 offset:26304
	s_waitcnt lgkmcnt(12)
	v_mfma_f32_16x16x32_bf16 v[136:139], v[214:217], v[198:201], v[136:139]
	v_mfma_f32_16x16x32_bf16 v[128:131], v[214:217], v[206:209], v[128:131]
	ds_read_b64_tr_b16 v[214:215], v238 offset:17632
	ds_read_b64_tr_b16 v[216:217], v238 offset:26336
	s_waitcnt lgkmcnt(12)
	v_mfma_f32_16x16x32_bf16 v[120:123], v[218:221], v[198:201], v[120:123]
	v_mfma_f32_16x16x32_bf16 v[112:115], v[218:221], v[206:209], v[112:115]
	ds_read_b64_tr_b16 v[218:219], v238 offset:17664
	ds_read_b64_tr_b16 v[220:221], v238 offset:26368
	s_waitcnt lgkmcnt(12)
	v_mfma_f32_16x16x32_bf16 v[108:111], v[202:205], v[198:201], v[108:111]
	v_mfma_f32_16x16x32_bf16 v[104:107], v[202:205], v[206:209], v[104:107]
	ds_read_b64_tr_b16 v[202:203], v238 offset:17696
	ds_read_b64_tr_b16 v[204:205], v238 offset:26400
	s_waitcnt lgkmcnt(12)
	v_mfma_f32_16x16x32_bf16 v[100:103], v[210:213], v[198:201], v[100:103]
	v_mfma_f32_16x16x32_bf16 v[96:99], v[210:213], v[206:209], v[96:99]
	ds_read_b64_tr_b16 v[210:211], v238 offset:17728
	ds_read_b64_tr_b16 v[212:213], v238 offset:26432
	s_waitcnt lgkmcnt(12)
	v_mfma_f32_16x16x32_bf16 v[92:95], v[224:227], v[198:201], v[92:95]
	v_mfma_f32_16x16x32_bf16 v[88:91], v[224:227], v[206:209], v[88:91]
	ds_read_b64_tr_b16 v[224:225], v238 offset:17760
	ds_read_b64_tr_b16 v[226:227], v238 offset:26464
	s_waitcnt lgkmcnt(12)
	v_mfma_f32_16x16x32_bf16 v[84:87], v[228:231], v[198:201], v[84:87]
	v_mfma_f32_16x16x32_bf16 v[80:83], v[228:231], v[206:209], v[80:83]
	ds_read_b64_tr_b16 v[228:229], v238 offset:17792
	ds_read_b64_tr_b16 v[230:231], v238 offset:26496
	s_waitcnt lgkmcnt(12)
	v_mfma_f32_16x16x32_bf16 v[76:79], v[232:235], v[198:201], v[76:79]
	v_mfma_f32_16x16x32_bf16 v[72:75], v[232:235], v[206:209], v[72:75]
	ds_read_b64_tr_b16 v[232:233], v238 offset:17824
	ds_read_b64_tr_b16 v[234:235], v238 offset:26528
	s_waitcnt lgkmcnt(12)
	v_mfma_f32_16x16x32_bf16 v[68:71], v[214:217], v[198:201], v[68:71]
	v_mfma_f32_16x16x32_bf16 v[64:67], v[214:217], v[206:209], v[64:67]
	ds_read_b64_tr_b16 v[214:215], v238 offset:17856
	ds_read_b64_tr_b16 v[216:217], v238 offset:26560
	s_waitcnt lgkmcnt(12)
	v_mfma_f32_16x16x32_bf16 v[60:63], v[218:221], v[198:201], v[60:63]
	v_mfma_f32_16x16x32_bf16 v[56:59], v[218:221], v[206:209], v[56:59]
	ds_read_b64_tr_b16 v[218:219], v238 offset:17888
	ds_read_b64_tr_b16 v[220:221], v238 offset:26592
	s_waitcnt lgkmcnt(12)
	v_mfma_f32_16x16x32_bf16 v[48:51], v[202:205], v[198:201], v[48:51]
	v_mfma_f32_16x16x32_bf16 v[40:43], v[202:205], v[206:209], v[40:43]
	s_waitcnt lgkmcnt(10)
	v_mfma_f32_16x16x32_bf16 v[44:47], v[210:213], v[198:201], v[44:47]
	v_mfma_f32_16x16x32_bf16 v[52:55], v[210:213], v[206:209], v[52:55]
	s_waitcnt lgkmcnt(8)
	v_mfma_f32_16x16x32_bf16 v[28:31], v[224:227], v[198:201], v[28:31]
	v_mfma_f32_16x16x32_bf16 v[36:39], v[224:227], v[206:209], v[36:39]
	s_waitcnt lgkmcnt(6)
	v_mfma_f32_16x16x32_bf16 v[16:19], v[228:231], v[198:201], v[16:19]
	v_mfma_f32_16x16x32_bf16 v[32:35], v[228:231], v[206:209], v[32:35]
	s_waitcnt lgkmcnt(4)
	v_mfma_f32_16x16x32_bf16 v[8:11], v[232:235], v[198:201], v[8:11]
	v_mfma_f32_16x16x32_bf16 v[24:27], v[232:235], v[206:209], v[24:27]
	s_waitcnt lgkmcnt(2)
	v_mfma_f32_16x16x32_bf16 v[4:7], v[214:217], v[198:201], v[4:7]
	v_mfma_f32_16x16x32_bf16 v[20:23], v[214:217], v[206:209], v[20:23]
	s_waitcnt lgkmcnt(0)
	v_mfma_f32_16x16x32_bf16 v[0:3], v[218:221], v[198:201], v[0:3]
	v_mfma_f32_16x16x32_bf16 v[12:15], v[218:221], v[206:209], v[12:15]

.LBB0_229:
	s_or_b64 exec, exec, s[0:1]
	s_waitcnt lgkmcnt(0)
	s_barrier
	ds_read_b32 v0, v181
	s_mov_b64 s[0:1], -1
	s_waitcnt lgkmcnt(0)
	v_cmp_lt_i32_e32 vcc, s25, v0
	v_readfirstlane_b32 s4, v0
	s_cbranch_vccnz .LBB0_224
	s_ashr_i32 s0, s4, 31
	s_lshr_b32 s0, s0, 23
	s_add_i32 s0, s4, s0
	s_and_b32 s0, s0, 0xfffffe00
	s_sub_i32 s6, s4, s0
	v_readfirstlane_b32 s0, v183
	s_ashr_i32 s7, s6, 5
	s_lshr_b32 s0, s0, 2
	s_sub_i32 s8, 15, s7
	s_and_b32 s9, s0, 0x3ffffff0
	s_lshl_b32 s0, s6, 8
	s_and_b32 s4, s6, 7
	s_lshl_b32 s5, s8, 7
	s_and_b32 s16, s0, 0x1800
	s_add_i32 s37, s9, s5
	s_add_i32 s10, s4, 1
	s_mul_i32 s0, s16, 0xc000
	s_add_u32 s0, s74, s0
	s_addc_u32 s1, s75, 0
	s_lshl_b32 s36, s4, 8
	s_mul_i32 s11, s8, 0x600000
	s_mul_hi_u32 s5, s5, 0xc000
	s_add_u32 s11, s0, s11
	s_addc_u32 s5, s1, s5
	s_lshl_b32 s4, s4, 9
	s_add_u32 s4, s11, s4
	s_addc_u32 s5, s5, 0
	v_mov_b32_e32 v149, v145
	v_lshl_add_u64 v[0:1], s[4:5], 0, v[148:149]
	v_lshl_add_u64 v[28:29], v[0:1], 0, s[18:19]
	v_mov_b32_e32 v151, v145
	v_lshl_add_u64 v[24:25], v[28:29], 0, v[150:151]
	v_add_co_u32_e32 v8, vcc, s27, v24
	v_mov_b32_e32 v153, v145
	s_nop 0
	v_addc_co_u32_e32 v9, vcc, 0, v25, vcc
	v_add_co_u32_e32 v16, vcc, s28, v24
	v_or_b32_e32 v33, s36, v174
	s_waitcnt lgkmcnt(0)
	s_barrier
	v_lshl_add_u64 v[4:5], v[28:29], 0, v[152:153]
	v_addc_co_u32_e32 v17, vcc, 0, v25, vcc
	global_load_dwordx4 v[0:3], v[24:25], off
	s_nop 0
	global_load_dwordx4 v[4:7], v[4:5], off
	v_add_co_u32_e32 v24, vcc, s29, v24
	v_lshlrev_b32_e32 v162, 1, v33
	v_mov_b32_e32 v163, v145
	v_or_b32_e32 v32, s36, v173
	v_mov_b32_e32 v155, v145
	v_mov_b32_e32 v157, v145
	v_addc_co_u32_e32 v25, vcc, 0, v25, vcc
	v_mov_b32_e32 v159, v145
	v_lshl_add_u64 v[48:49], s[0:1], 0, v[162:163]
	v_lshl_add_u64 v[12:13], v[28:29], 0, v[154:155]
	v_lshl_add_u64 v[20:21], v[28:29], 0, v[156:157]
	v_lshl_add_u64 v[28:29], v[28:29], 0, v[158:159]
	v_lshlrev_b32_e32 v144, 1, v32
	v_add_co_u32_e32 v44, vcc, s30, v48
	global_load_dwordx4 v[8:11], v[8:9], off
	s_nop 0
	global_load_dwordx4 v[12:15], v[12:13], off
	s_nop 0
	global_load_dwordx4 v[16:19], v[16:17], off
	s_nop 0
	global_load_dwordx4 v[20:23], v[20:21], off
	v_addc_co_u32_e32 v45, vcc, 0, v49, vcc
	global_load_dwordx4 v[24:27], v[24:25], off
	v_lshl_add_u64 v[50:51], s[0:1], 0, v[144:145]
	global_load_dwordx4 v[28:31], v[28:29], off
	s_nop 0
	global_load_dwordx4 v[32:35], v144, s[0:1]
	global_load_dwordx4 v[36:39], v144, s[0:1] offset:256
	s_lshl_b32 s38, s8, 2
	v_add_co_u32_e32 v50, vcc, s27, v50
	s_add_i32 s38, s38, 4
	global_load_dwordx4 v[40:43], v162, s[0:1]
	v_addc_co_u32_e32 v51, vcc, 0, v51, vcc
	global_load_dwordx4 v[44:47], v[44:45], off
	s_add_u32 s0, s0, 0x180000
	v_add_co_u32_e32 v48, vcc, s31, v48
	s_addc_u32 s1, s1, 0
	s_nop 0
	v_addc_co_u32_e32 v49, vcc, 0, v49, vcc
	global_load_dwordx4 v[116:119], v[50:51], off offset:256
	global_load_dwordx4 v[132:135], v[48:49], off
	global_load_dwordx4 v[124:127], v144, s[0:1]
	global_load_dwordx4 v[140:143], v162, s[0:1]
	v_cvt_f32_ubyte0_e32 v48, s10
	s_bfe_u32 s0, s6, 0x20003
	v_exp_f32_e64 v48, -v48
	s_or_b32 s41, s37, 15
	s_mul_i32 s0, s0, 0x6000000
	s_add_u32 s22, s70, s0
	s_addc_u32 s23, s71, 0
	s_lshl_b32 s0, s7, 2
	s_sub_i32 s42, s0, 64
	s_lshl_b32 s0, s7, 7
	v_mul_f32_e32 v149, 0x3fb8aa3b, v48
	s_mov_b32 s39, 31
	s_mov_b32 s40, 2
	v_mul_f32_e32 v151, 0x41800000, v149
	s_waitcnt vmcnt(15)
	ds_write_b128 v184, v[0:3]
	s_waitcnt vmcnt(14)
	ds_write_b128 v185, v[4:7]
	s_waitcnt vmcnt(13)
	ds_write_b128 v184, v[8:11] offset:8704
	s_waitcnt vmcnt(12)
	ds_write_b128 v186, v[12:15]
	s_waitcnt vmcnt(11)
	ds_write_b128 v184, v[16:19] offset:17408
	s_waitcnt vmcnt(10)
	ds_write_b128 v187, v[20:23]
	s_waitcnt vmcnt(9)
	ds_write_b128 v184, v[24:27] offset:26112
	s_waitcnt vmcnt(8)
	ds_write_b128 v188, v[28:31]
	s_waitcnt vmcnt(7)
	ds_write_b128 v189, v[32:35]
	s_waitcnt vmcnt(6)
	ds_write_b128 v189, v[36:39] offset:8704
	s_waitcnt vmcnt(5)
	ds_write_b128 v190, v[40:43] offset:17408
	s_waitcnt vmcnt(4)
	ds_write_b128 v190, v[44:47] offset:26112
	v_or_b32_e32 v0, s9, v169
	s_waitcnt lgkmcnt(0)
	s_barrier
	v_mul_lo_u32 v0, v0, s3
	v_add_u32_e32 v1, s9, v180
	v_mov_b32_e32 v40, v145
	v_mov_b32_e32 v41, v145
	v_mov_b32_e32 v42, v145
	v_mov_b32_e32 v43, v145
	v_subrev_u32_e32 v194, s0, v1
	v_add_u32_e32 v195, v177, v0
	v_mov_b64_e32 v[58:59], v[42:43]
	v_mov_b64_e32 v[66:67], v[42:43]
	v_mov_b64_e32 v[74:75], v[42:43]
	v_mov_b64_e32 v[82:83], v[42:43]
	v_mov_b64_e32 v[90:91], v[42:43]
	v_mov_b64_e32 v[98:99], v[42:43]
	v_mov_b64_e32 v[106:107], v[42:43]
	v_mov_b64_e32 v[114:115], v[42:43]
	v_mov_b64_e32 v[130:131], v[42:43]
	v_mov_b64_e32 v[0:1], v[40:41]
	v_mov_b64_e32 v[4:5], v[40:41]
	v_mov_b64_e32 v[8:9], v[40:41]
	v_mov_b64_e32 v[16:17], v[40:41]
	v_mov_b64_e32 v[28:29], v[40:41]
	v_mov_b64_e32 v[46:47], v[42:43]
	v_mov_b64_e32 v[50:51], v[42:43]
	v_mov_b64_e32 v[62:63], v[42:43]
	v_mov_b64_e32 v[70:71], v[42:43]
	v_mov_b64_e32 v[78:79], v[42:43]
	v_mov_b64_e32 v[86:87], v[42:43]
	v_mov_b64_e32 v[94:95], v[42:43]
	v_mov_b64_e32 v[102:103], v[42:43]
	v_mov_b64_e32 v[110:111], v[42:43]
	v_mov_b64_e32 v[122:123], v[42:43]
	v_mov_b64_e32 v[138:139], v[42:43]
	v_mov_b64_e32 v[54:55], v[42:43]
	v_mov_b64_e32 v[36:37], v[40:41]
	v_mov_b64_e32 v[32:33], v[40:41]
	v_mov_b64_e32 v[24:25], v[40:41]
	v_mov_b64_e32 v[20:21], v[40:41]
	v_mov_b64_e32 v[12:13], v[40:41]
	v_mul_f32_e32 v153, 0, v149
	v_add_f32_e32 v155, v149, v149
	v_mul_f32_e32 v157, 0x40400000, v149
	v_mul_f32_e32 v159, 0x41880000, v149
	v_mul_f32_e32 v161, 0x41900000, v149
	v_mul_f32_e32 v193, 0x41980000, v149
	v_mov_b32_e32 v164, v145
	v_mov_b32_e32 v165, v145
	v_mov_b32_e32 v166, 0xf149f2ca
	v_mov_b64_e32 v[56:57], v[40:41]
	v_mov_b64_e32 v[64:65], v[40:41]
	v_mov_b64_e32 v[72:73], v[40:41]
	v_mov_b64_e32 v[80:81], v[40:41]
	v_mov_b64_e32 v[88:89], v[40:41]
	v_mov_b64_e32 v[96:97], v[40:41]
	v_mov_b64_e32 v[104:105], v[40:41]
	v_mov_b64_e32 v[112:113], v[40:41]
	v_mov_b64_e32 v[128:129], v[40:41]
	v_mov_b64_e32 v[2:3], v[42:43]
	v_mov_b64_e32 v[6:7], v[42:43]
	v_mov_b64_e32 v[10:11], v[42:43]
	v_mov_b64_e32 v[18:19], v[42:43]
	v_mov_b64_e32 v[30:31], v[42:43]
	v_mov_b64_e32 v[44:45], v[40:41]
	v_mov_b64_e32 v[48:49], v[40:41]
	v_mov_b64_e32 v[60:61], v[40:41]
	v_mov_b64_e32 v[68:69], v[40:41]
	v_mov_b64_e32 v[76:77], v[40:41]
	v_mov_b64_e32 v[84:85], v[40:41]
	v_mov_b64_e32 v[92:93], v[40:41]
	v_mov_b64_e32 v[100:101], v[40:41]
	v_mov_b64_e32 v[108:109], v[40:41]
	v_mov_b64_e32 v[120:121], v[40:41]
	v_mov_b64_e32 v[136:137], v[40:41]
	v_mov_b32_e32 v167, 0xf149f2ca
	v_mov_b64_e32 v[52:53], v[40:41]
	v_mov_b64_e32 v[38:39], v[42:43]
	v_mov_b64_e32 v[34:35], v[42:43]
	v_mov_b64_e32 v[26:27], v[42:43]
	v_mov_b64_e32 v[22:23], v[42:43]
	v_mov_b64_e32 v[14:15], v[42:43]
	v_readfirstlane_b32 s5, v149
	v_readfirstlane_b32 s6, v155
	v_readfirstlane_b32 s7, v157
	v_readfirstlane_b32 s8, v151
	v_readfirstlane_b32 s9, v159
	v_readfirstlane_b32 s10, v161
	v_readfirstlane_b32 s11, v193
	s_mov_b32 s4, 0
	s_mov_b32 s12, 0x3e0293ee
	s_mov_b32 s13, 0x3e0293ee
	s_mov_b32 s91, 0
	v_readfirstlane_b32 s86, v149
	v_readfirstlane_b32 s87, v151
	v_readfirstlane_b32 s88, v155
	v_readfirstlane_b32 s89, v157
	v_readfirstlane_b32 s90, v159
	ds_read_b128 v[240:243], v195
	ds_read_b128 v[244:247], v195 offset:64
	ds_read_b128 v[248:251], v195 offset:128
	ds_read_b128 v[252:255], v195 offset:192
	ds_read_b128 v[148:151], v195 offset:34816
	ds_read_b128 v[152:155], v195 offset:34880
	ds_read_b128 v[156:159], v195 offset:34944
	ds_read_b128 v[184:187], v195 offset:35008
	s_waitcnt lgkmcnt(0)
.LBB0_231:
	s_bitcmp1_b32 s40, 0
	s_cselect_b32 s43, 0x8800, 0
	s_cmp_lt_u32 s97, 4
	s_cbranch_scc1 .Latt_top_done
	s_add_i32 s0, s40, -1
	s_cmp_ge_u32 s0, s38
	s_cbranch_scc1 .Latt_stage_done
	s_sub_i32 s0, 0, s43
	v_add_u32_e32 v238, s0, v175
	s_waitcnt vmcnt(1)
	ds_write_b128 v238, v[124:127] offset:34816
	ds_write_b128 v238, v[116:119] offset:43520
	s_add_i32 s1, s91, 0x8800
	s_cmp_eq_u32 s1, 0x19800
	s_cselect_b32 s1, 0, s1
	v_add_u32_e32 v238, s1, v176
	s_cmp_ge_u32 s40, s38
	s_waitcnt vmcnt(0)
	ds_write_b128 v238, v[140:143] offset:17408
	ds_write_b128 v238, v[132:135] offset:26112
	s_cbranch_scc1 .Latt_stage_done
	v_lshl_add_u64 v[116:117], s[22:23], 0, v[144:145]
	v_add_co_u32_e32 v116, vcc, 0x14400000, v116
	v_lshl_add_u64 v[132:133], s[22:23], 0, v[162:163]
	s_nop 0
	v_addc_co_u32_e32 v117, vcc, 0, v117, vcc
	v_add_co_u32_e32 v134, vcc, 0x14400000, v132
	global_load_dwordx4 v[124:127], v[116:117], off
	s_nop 0
	global_load_dwordx4 v[116:119], v[116:117], off offset:256
	v_addc_co_u32_e32 v135, vcc, 0, v133, vcc
	v_add_co_u32_e32 v132, vcc, 0x144c0000, v132
	s_nop 1
	v_addc_co_u32_e32 v133, vcc, 0, v133, vcc
	global_load_dwordx4 v[140:143], v[134:135], off
	s_nop 0
	global_load_dwordx4 v[132:135], v[132:133], off
.Latt_stage_done:
	s_sub_i32 s0, s39, 63
	s_cmp_gt_u32 s0, s41
	s_cbranch_scc1 .Latt_top_done
	s_sub_i32 s0, s91, 0x8800
	s_cmp_eq_u32 s91, 0
	s_cselect_b32 s0, 0x11000, s0
	v_add_u32_e32 v238, s0, v179
	ds_read_b64_tr_b16 v[214:215], v238 offset:17408
	ds_read_b64_tr_b16 v[216:217], v238 offset:26112
	ds_read_b64_tr_b16 v[218:219], v238 offset:17440
	ds_read_b64_tr_b16 v[220:221], v238 offset:26144
	ds_read_b64_tr_b16 v[202:203], v238 offset:17472
	ds_read_b64_tr_b16 v[204:205], v238 offset:26176
	ds_read_b64_tr_b16 v[210:211], v238 offset:17504
	ds_read_b64_tr_b16 v[212:213], v238 offset:26208
	ds_read_b64_tr_b16 v[224:225], v238 offset:17536
	ds_read_b64_tr_b16 v[226:227], v238 offset:26240
	ds_read_b64_tr_b16 v[228:229], v238 offset:17568
	ds_read_b64_tr_b16 v[230:231], v238 offset:26272
	ds_read_b64_tr_b16 v[232:233], v238 offset:17600
	ds_read_b64_tr_b16 v[234:235], v238 offset:26304
	s_waitcnt lgkmcnt(12)
	v_mfma_f32_16x16x32_bf16 v[136:139], v[214:217], v[198:201], v[136:139]
	v_mfma_f32_16x16x32_bf16 v[128:131], v[214:217], v[206:209], v[128:131]
	ds_read_b64_tr_b16 v[214:215], v238 offset:17632
	ds_read_b64_tr_b16 v[216:217], v238 offset:26336
	s_waitcnt lgkmcnt(12)
	v_mfma_f32_16x16x32_bf16 v[120:123], v[218:221], v[198:201], v[120:123]
	v_mfma_f32_16x16x32_bf16 v[112:115], v[218:221], v[206:209], v[112:115]
	ds_read_b64_tr_b16 v[218:219], v238 offset:17664
	ds_read_b64_tr_b16 v[220:221], v238 offset:26368
	s_waitcnt lgkmcnt(12)
	v_mfma_f32_16x16x32_bf16 v[108:111], v[202:205], v[198:201], v[108:111]
	v_mfma_f32_16x16x32_bf16 v[104:107], v[202:205], v[206:209], v[104:107]
	ds_read_b64_tr_b16 v[202:203], v238 offset:17696
	ds_read_b64_tr_b16 v[204:205], v238 offset:26400
	s_waitcnt lgkmcnt(12)
	v_mfma_f32_16x16x32_bf16 v[100:103], v[210:213], v[198:201], v[100:103]
	v_mfma_f32_16x16x32_bf16 v[96:99], v[210:213], v[206:209], v[96:99]
	ds_read_b64_tr_b16 v[210:211], v238 offset:17728
	ds_read_b64_tr_b16 v[212:213], v238 offset:26432
	s_waitcnt lgkmcnt(12)
	v_mfma_f32_16x16x32_bf16 v[92:95], v[224:227], v[198:201], v[92:95]
	v_mfma_f32_16x16x32_bf16 v[88:91], v[224:227], v[206:209], v[88:91]
	ds_read_b64_tr_b16 v[224:225], v238 offset:17760
	ds_read_b64_tr_b16 v[226:227], v238 offset:26464
	s_waitcnt lgkmcnt(12)
	v_mfma_f32_16x16x32_bf16 v[84:87], v[228:231], v[198:201], v[84:87]
	v_mfma_f32_16x16x32_bf16 v[80:83], v[228:231], v[206:209], v[80:83]
	ds_read_b64_tr_b16 v[228:229], v238 offset:17792
	ds_read_b64_tr_b16 v[230:231], v238 offset:26496
	s_waitcnt lgkmcnt(12)
	v_mfma_f32_16x16x32_bf16 v[76:79], v[232:235], v[198:201], v[76:79]
	v_mfma_f32_16x16x32_bf16 v[72:75], v[232:235], v[206:209], v[72:75]
	ds_read_b64_tr_b16 v[232:233], v238 offset:17824
	ds_read_b64_tr_b16 v[234:235], v238 offset:26528
	s_waitcnt lgkmcnt(12)
	v_mfma_f32_16x16x32_bf16 v[68:71], v[214:217], v[198:201], v[68:71]
	v_mfma_f32_16x16x32_bf16 v[64:67], v[214:217], v[206:209], v[64:67]
	ds_read_b64_tr_b16 v[214:215], v238 offset:17856
	ds_read_b64_tr_b16 v[216:217], v238 offset:26560
	s_waitcnt lgkmcnt(12)
	v_mfma_f32_16x16x32_bf16 v[60:63], v[218:221], v[198:201], v[60:63]
	v_mfma_f32_16x16x32_bf16 v[56:59], v[218:221], v[206:209], v[56:59]
	ds_read_b64_tr_b16 v[218:219], v238 offset:17888
	ds_read_b64_tr_b16 v[220:221], v238 offset:26592
	s_waitcnt lgkmcnt(12)
	v_mfma_f32_16x16x32_bf16 v[48:51], v[202:205], v[198:201], v[48:51]
	v_mfma_f32_16x16x32_bf16 v[40:43], v[202:205], v[206:209], v[40:43]
	s_waitcnt lgkmcnt(10)
	v_mfma_f32_16x16x32_bf16 v[44:47], v[210:213], v[198:201], v[44:47]
	v_mfma_f32_16x16x32_bf16 v[52:55], v[210:213], v[206:209], v[52:55]
	s_waitcnt lgkmcnt(8)
	v_mfma_f32_16x16x32_bf16 v[28:31], v[224:227], v[198:201], v[28:31]
	v_mfma_f32_16x16x32_bf16 v[36:39], v[224:227], v[206:209], v[36:39]
	s_waitcnt lgkmcnt(6)
	v_mfma_f32_16x16x32_bf16 v[16:19], v[228:231], v[198:201], v[16:19]
	v_mfma_f32_16x16x32_bf16 v[32:35], v[228:231], v[206:209], v[32:35]
	s_waitcnt lgkmcnt(4)
	v_mfma_f32_16x16x32_bf16 v[8:11], v[232:235], v[198:201], v[8:11]
	v_mfma_f32_16x16x32_bf16 v[24:27], v[232:235], v[206:209], v[24:27]
	s_waitcnt lgkmcnt(2)
	v_mfma_f32_16x16x32_bf16 v[4:7], v[214:217], v[198:201], v[4:7]
	v_mfma_f32_16x16x32_bf16 v[20:23], v[214:217], v[206:209], v[20:23]
	s_waitcnt lgkmcnt(0)
	v_mfma_f32_16x16x32_bf16 v[0:3], v[218:221], v[198:201], v[0:3]
	v_mfma_f32_16x16x32_bf16 v[12:15], v[218:221], v[206:209], v[12:15]

.LBB0_234:
	s_cmp_ge_u32 s97, 4
	s_cbranch_scc1 .Latt_btail
	v_add_u32_e32 v238, s91, v179
	ds_read_b64_tr_b16 v[214:215], v238 offset:17408
	ds_read_b64_tr_b16 v[216:217], v238 offset:26112
	ds_read_b64_tr_b16 v[218:219], v238 offset:17440
	ds_read_b64_tr_b16 v[220:221], v238 offset:26144
	v_pk_add_f32 v[198:199], v[198:199], v[196:197] op_sel_hi:[1,0] neg_lo:[0,1] neg_hi:[0,1]
	v_pk_add_f32 v[200:201], v[200:201], v[196:197] op_sel_hi:[1,0] neg_lo:[0,1] neg_hi:[0,1]
	v_pk_add_f32 v[202:203], v[202:203], v[196:197] op_sel_hi:[1,0] neg_lo:[0,1] neg_hi:[0,1]
	v_pk_add_f32 v[204:205], v[204:205], v[196:197] op_sel_hi:[1,0] neg_lo:[0,1] neg_hi:[0,1]
	v_pk_add_f32 v[206:207], v[206:207], v[196:197] op_sel:[0,1] op_sel_hi:[1,1] neg_lo:[0,1] neg_hi:[0,1]
	v_pk_add_f32 v[208:209], v[208:209], v[196:197] op_sel:[0,1] op_sel_hi:[1,1] neg_lo:[0,1] neg_hi:[0,1]
	v_pk_add_f32 v[210:211], v[210:211], v[196:197] op_sel:[0,1] op_sel_hi:[1,1] neg_lo:[0,1] neg_hi:[0,1]
	v_pk_add_f32 v[212:213], v[212:213], v[196:197] op_sel:[0,1] op_sel_hi:[1,1] neg_lo:[0,1] neg_hi:[0,1]
	v_exp_f32_e32 v231, v202
	v_exp_f32_e32 v233, v203
	v_exp_f32_e32 v235, v204
	v_exp_f32_e32 v237, v205
	v_exp_f32_e32 v230, v210
	v_exp_f32_e32 v232, v211
	v_exp_f32_e32 v234, v212
	v_exp_f32_e32 v236, v213
	ds_read_b64_tr_b16 v[202:203], v238 offset:17472
	ds_read_b64_tr_b16 v[204:205], v238 offset:26176
	ds_read_b64_tr_b16 v[210:211], v238 offset:17504
	ds_read_b64_tr_b16 v[212:213], v238 offset:26208
	v_exp_f32_e32 v223, v198
	v_exp_f32_e32 v225, v199
	v_exp_f32_e32 v227, v200
	v_exp_f32_e32 v229, v201
	v_exp_f32_e32 v222, v206
	v_exp_f32_e32 v224, v207
	v_exp_f32_e32 v226, v208
	v_exp_f32_e32 v228, v209
	v_cvt_pk_bf16_f32 v198, v223, v225
	v_cvt_pk_bf16_f32 v199, v227, v229
	v_cvt_pk_bf16_f32 v200, v231, v233
	v_cvt_pk_bf16_f32 v201, v235, v237
	v_cvt_pk_bf16_f32 v206, v222, v224
	v_cvt_pk_bf16_f32 v207, v226, v228
	v_cvt_pk_bf16_f32 v208, v230, v232
	v_cvt_pk_bf16_f32 v209, v234, v236
	v_pk_add_f32 v[222:223], v[224:225], v[222:223]
	v_pk_add_f32 v[222:223], v[226:227], v[222:223]
	v_pk_add_f32 v[222:223], v[228:229], v[222:223]
	v_pk_add_f32 v[222:223], v[230:231], v[222:223]
	v_pk_add_f32 v[222:223], v[232:233], v[222:223]
	v_pk_add_f32 v[222:223], v[234:235], v[222:223]
	v_pk_add_f32 v[222:223], v[236:237], v[222:223]
	ds_read_b64_tr_b16 v[224:225], v238 offset:17536
	ds_read_b64_tr_b16 v[226:227], v238 offset:26240
	ds_read_b64_tr_b16 v[228:229], v238 offset:17568
	ds_read_b64_tr_b16 v[230:231], v238 offset:26272
	ds_read_b64_tr_b16 v[232:233], v238 offset:17600
	ds_read_b64_tr_b16 v[234:235], v238 offset:26304
	s_waitcnt lgkmcnt(12)
	v_mfma_f32_16x16x32_bf16 v[136:139], v[214:217], v[198:201], v[136:139]
	v_mfma_f32_16x16x32_bf16 v[128:131], v[214:217], v[206:209], v[128:131]
	ds_read_b64_tr_b16 v[214:215], v238 offset:17632
	ds_read_b64_tr_b16 v[216:217], v238 offset:26336
	s_waitcnt lgkmcnt(12)
	v_mfma_f32_16x16x32_bf16 v[120:123], v[218:221], v[198:201], v[120:123]
	v_mfma_f32_16x16x32_bf16 v[112:115], v[218:221], v[206:209], v[112:115]
	ds_read_b64_tr_b16 v[218:219], v238 offset:17664
	ds_read_b64_tr_b16 v[220:221], v238 offset:26368
	v_fma_f32 v164, v164, v166, v222
	v_fma_f32 v165, v165, v167, v223
	s_waitcnt lgkmcnt(12)
	v_mfma_f32_16x16x32_bf16 v[108:111], v[202:205], v[198:201], v[108:111]
	v_mfma_f32_16x16x32_bf16 v[104:107], v[202:205], v[206:209], v[104:107]
	ds_read_b64_tr_b16 v[202:203], v238 offset:17696
	ds_read_b64_tr_b16 v[204:205], v238 offset:26400
	s_waitcnt lgkmcnt(12)
	v_mfma_f32_16x16x32_bf16 v[100:103], v[210:213], v[198:201], v[100:103]
	v_mfma_f32_16x16x32_bf16 v[96:99], v[210:213], v[206:209], v[96:99]
	ds_read_b64_tr_b16 v[210:211], v238 offset:17728
	ds_read_b64_tr_b16 v[212:213], v238 offset:26432
	s_waitcnt lgkmcnt(12)
	v_mfma_f32_16x16x32_bf16 v[92:95], v[224:227], v[198:201], v[92:95]
	v_mfma_f32_16x16x32_bf16 v[88:91], v[224:227], v[206:209], v[88:91]
	ds_read_b64_tr_b16 v[224:225], v238 offset:17760
	ds_read_b64_tr_b16 v[226:227], v238 offset:26464
	s_waitcnt lgkmcnt(12)
	v_mfma_f32_16x16x32_bf16 v[84:87], v[228:231], v[198:201], v[84:87]
	v_mfma_f32_16x16x32_bf16 v[80:83], v[228:231], v[206:209], v[80:83]
	ds_read_b64_tr_b16 v[228:229], v238 offset:17792
	ds_read_b64_tr_b16 v[230:231], v238 offset:26496
	s_waitcnt lgkmcnt(12)
	v_mfma_f32_16x16x32_bf16 v[76:79], v[232:235], v[198:201], v[76:79]
	v_mfma_f32_16x16x32_bf16 v[72:75], v[232:235], v[206:209], v[72:75]
	ds_read_b64_tr_b16 v[232:233], v238 offset:17824
	ds_read_b64_tr_b16 v[234:235], v238 offset:26528
	s_waitcnt lgkmcnt(12)
	v_mfma_f32_16x16x32_bf16 v[68:71], v[214:217], v[198:201], v[68:71]
	v_mfma_f32_16x16x32_bf16 v[64:67], v[214:217], v[206:209], v[64:67]
	ds_read_b64_tr_b16 v[214:215], v238 offset:17856
	ds_read_b64_tr_b16 v[216:217], v238 offset:26560
	s_waitcnt lgkmcnt(12)
	v_mfma_f32_16x16x32_bf16 v[60:63], v[218:221], v[198:201], v[60:63]
	v_mfma_f32_16x16x32_bf16 v[56:59], v[218:221], v[206:209], v[56:59]
	ds_read_b64_tr_b16 v[218:219], v238 offset:17888
	ds_read_b64_tr_b16 v[220:221], v238 offset:26592
	s_waitcnt lgkmcnt(12)
	v_mfma_f32_16x16x32_bf16 v[48:51], v[202:205], v[198:201], v[48:51]
	v_mfma_f32_16x16x32_bf16 v[40:43], v[202:205], v[206:209], v[40:43]
	s_waitcnt lgkmcnt(10)
	v_mfma_f32_16x16x32_bf16 v[44:47], v[210:213], v[198:201], v[44:47]
	v_mfma_f32_16x16x32_bf16 v[52:55], v[210:213], v[206:209], v[52:55]
	s_waitcnt lgkmcnt(8)
	v_mfma_f32_16x16x32_bf16 v[28:31], v[224:227], v[198:201], v[28:31]
	v_mfma_f32_16x16x32_bf16 v[36:39], v[224:227], v[206:209], v[36:39]
	s_waitcnt lgkmcnt(6)
	v_mfma_f32_16x16x32_bf16 v[16:19], v[228:231], v[198:201], v[16:19]
	v_mfma_f32_16x16x32_bf16 v[32:35], v[228:231], v[206:209], v[32:35]
	s_waitcnt lgkmcnt(4)
	v_mfma_f32_16x16x32_bf16 v[8:11], v[232:235], v[198:201], v[8:11]
	v_mfma_f32_16x16x32_bf16 v[24:27], v[232:235], v[206:209], v[24:27]
	s_waitcnt lgkmcnt(2)
	v_mfma_f32_16x16x32_bf16 v[4:7], v[214:217], v[198:201], v[4:7]
	v_mfma_f32_16x16x32_bf16 v[20:23], v[214:217], v[206:209], v[20:23]
	s_waitcnt lgkmcnt(0)
	v_mfma_f32_16x16x32_bf16 v[0:3], v[218:221], v[198:201], v[0:3]
	v_mfma_f32_16x16x32_bf16 v[12:15], v[218:221], v[206:209], v[12:15]
.Latt_pvend:
	s_add_i32 s0, s40, -1
	s_cmp_ge_u32 s0, s38
	s_cbranch_scc0 .LBB0_236
	s_branch .LBB0_238
.Latt_btail:
	v_pk_add_f32 v[198:199], v[198:199], v[196:197] op_sel_hi:[1,0] neg_lo:[0,1] neg_hi:[0,1]
	v_pk_add_f32 v[200:201], v[200:201], v[196:197] op_sel_hi:[1,0] neg_lo:[0,1] neg_hi:[0,1]
	v_pk_add_f32 v[202:203], v[202:203], v[196:197] op_sel_hi:[1,0] neg_lo:[0,1] neg_hi:[0,1]
	v_pk_add_f32 v[204:205], v[204:205], v[196:197] op_sel_hi:[1,0] neg_lo:[0,1] neg_hi:[0,1]
	v_pk_add_f32 v[206:207], v[206:207], v[196:197] op_sel:[0,1] op_sel_hi:[1,1] neg_lo:[0,1] neg_hi:[0,1]
	v_pk_add_f32 v[208:209], v[208:209], v[196:197] op_sel:[0,1] op_sel_hi:[1,1] neg_lo:[0,1] neg_hi:[0,1]
	v_pk_add_f32 v[210:211], v[210:211], v[196:197] op_sel:[0,1] op_sel_hi:[1,1] neg_lo:[0,1] neg_hi:[0,1]
	v_pk_add_f32 v[212:213], v[212:213], v[196:197] op_sel:[0,1] op_sel_hi:[1,1] neg_lo:[0,1] neg_hi:[0,1]
	v_exp_f32_e32 v231, v202
	v_exp_f32_e32 v233, v203
	v_exp_f32_e32 v235, v204
	v_exp_f32_e32 v237, v205
	v_exp_f32_e32 v230, v210
	v_exp_f32_e32 v232, v211
	v_exp_f32_e32 v234, v212
	v_exp_f32_e32 v236, v213
	v_exp_f32_e32 v223, v198
	v_exp_f32_e32 v225, v199
	v_exp_f32_e32 v227, v200
	v_exp_f32_e32 v229, v201
	v_exp_f32_e32 v222, v206
	v_exp_f32_e32 v224, v207
	v_exp_f32_e32 v226, v208
	v_exp_f32_e32 v228, v209
	v_cvt_pk_bf16_f32 v198, v223, v225
	v_cvt_pk_bf16_f32 v199, v227, v229
	v_cvt_pk_bf16_f32 v200, v231, v233
	v_cvt_pk_bf16_f32 v201, v235, v237
	v_cvt_pk_bf16_f32 v206, v222, v224
	v_cvt_pk_bf16_f32 v207, v226, v228
	v_cvt_pk_bf16_f32 v208, v230, v232
	v_cvt_pk_bf16_f32 v209, v234, v236
	v_pk_add_f32 v[222:223], v[224:225], v[222:223]
	v_pk_add_f32 v[222:223], v[226:227], v[222:223]
	v_pk_add_f32 v[222:223], v[228:229], v[222:223]
	v_pk_add_f32 v[222:223], v[230:231], v[222:223]
	v_pk_add_f32 v[222:223], v[232:233], v[222:223]
	v_pk_add_f32 v[222:223], v[234:235], v[222:223]
	v_pk_add_f32 v[222:223], v[236:237], v[222:223]
	v_fma_f32 v164, v164, v166, v222
	v_fma_f32 v165, v165, v167, v223
	s_branch .Latt_pvend

.LBB0_236:
	s_cmp_ge_u32 s97, 4
	s_cbranch_scc1 .LBB0_238
	s_sub_i32 s0, 0, s43
	v_add_u32_e32 v166, s0, v175
	s_waitcnt vmcnt(1)
	ds_write_b128 v166, v[124:127] offset:34816
	ds_write_b128 v166, v[116:119] offset:43520
	s_add_i32 s1, s91, 0x8800
	s_cmp_eq_u32 s1, 0x19800
	s_cselect_b32 s1, 0, s1
	v_add_u32_e32 v166, s1, v176
	s_cmp_ge_u32 s40, s38
	s_waitcnt vmcnt(0)
	ds_write_b128 v166, v[140:143] offset:17408
	ds_write_b128 v166, v[132:135] offset:26112
	s_cbranch_scc1 .LBB0_238
	v_lshl_add_u64 v[116:117], s[22:23], 0, v[144:145]
	v_add_co_u32_e32 v116, vcc, 0x14400000, v116
	v_lshl_add_u64 v[132:133], s[22:23], 0, v[162:163]
	s_nop 0
	v_addc_co_u32_e32 v117, vcc, 0, v117, vcc
	v_add_co_u32_e32 v134, vcc, 0x14400000, v132
	global_load_dwordx4 v[124:127], v[116:117], off
	s_nop 0
	global_load_dwordx4 v[116:119], v[116:117], off offset:256
	v_addc_co_u32_e32 v135, vcc, 0, v133, vcc
	v_add_co_u32_e32 v132, vcc, 0x144c0000, v132
	s_nop 1
	v_addc_co_u32_e32 v133, vcc, 0, v133, vcc
	global_load_dwordx4 v[140:143], v[134:135], off
	s_nop 0
	global_load_dwordx4 v[132:135], v[132:133], off
.LBB0_238:
	s_add_u32 s22, s22, 0x180000
	s_waitcnt lgkmcnt(0)
	s_barrier
	s_addc_u32 s23, s23, 0
	s_add_i32 s91, s91, 0x8800
	s_cmp_eq_u32 s91, 0x19800
	s_cselect_b32 s91, 0, s91
	s_add_i32 s40, s40, 1
	s_add_i32 s0, s42, s40
	s_add_i32 s39, s39, 32
	s_cmp_lg_u32 s0, 2
	v_subrev_u32_e32 v194, 32, v194
	s_cbranch_scc0 .LBB0_223
	v_mov_b32_e32 v166, v197
	v_mov_b32_e32 v167, v196
	s_branch .LBB0_231
